# speedup vs baseline: 1.0064x; 1.0038x over previous
; __device__ __forceinline__ void transpose_item(const float* __restrict__ W, int K, int N, int NV, bf16_t* __restrict__ WT, LAS float* scr, int item, int nblk, int lane, int mode, const float* __restrict__ kscale) {
;     const int kb = item / nblk, nb = item % nblk, k0 = 64 * kb, n0 = 32 * nb;
;     const int nd = n0 + (lane & 31); const bool valid = nd < NV; const int ns = valid ? srccol(mode, nd) : 0;
; #pragma unroll 8
;     for (int i = 0; i < 32; ++i) { const int kk = 2 * i + (lane >> 5); float v = valid ? W[(size_t)(k0 + kk) * N + ns] : 0.f; if (kscale) v *= kscale[k0 + kk]; scr[kk * 33 + (lane & 31)] = v; }
.LBB0_82:
.LBB0_83:
	v_lshl_add_u64 v[60:61], s[62:63], 0, v[24:25]
	v_lshl_add_u64 v[40:41], v[38:39], 0, s[58:59]
	global_load_dword v100, v[40:41], off
	v_lshl_add_u64 v[58:59], s[62:63], 0, v[6:7]
	global_load_dword v116, v[58:59], off
	v_lshl_add_u64 v[40:41], v[36:37], 0, s[58:59]
	global_load_dword v101, v[40:41], off
	global_load_dword v117, v[60:61], off offset:8
	v_lshl_add_u64 v[40:41], v[34:35], 0, s[58:59]
	global_load_dword v102, v[40:41], off
	global_load_dword v118, v[60:61], off offset:16
	v_lshl_add_u64 v[40:41], v[32:33], 0, s[58:59]
	global_load_dword v103, v[40:41], off
	global_load_dword v119, v[60:61], off offset:24
	v_lshl_add_u64 v[40:41], v[30:31], 0, s[58:59]
	global_load_dword v104, v[40:41], off
	global_load_dword v120, v[60:61], off offset:32
	v_lshl_add_u64 v[40:41], v[28:29], 0, s[58:59]
	global_load_dword v105, v[40:41], off
	global_load_dword v121, v[60:61], off offset:40
	v_lshl_add_u64 v[40:41], v[26:27], 0, s[58:59]
	global_load_dword v106, v[40:41], off
	global_load_dword v122, v[60:61], off offset:48
	v_lshl_add_u64 v[40:41], v[22:23], 0, s[58:59]
	global_load_dword v107, v[40:41], off
	global_load_dword v123, v[60:61], off offset:56
	s_add_u32 s58, s58, 0x20000
	s_addc_u32 s59, s59, 0
	s_add_u32 s62, s62, 64
	s_addc_u32 s63, s63, 0
	v_lshl_add_u64 v[60:61], s[62:63], 0, v[24:25]
	v_lshl_add_u64 v[40:41], v[38:39], 0, s[58:59]
	global_load_dword v108, v[40:41], off
	v_lshl_add_u64 v[58:59], s[62:63], 0, v[6:7]
	global_load_dword v124, v[58:59], off
	v_lshl_add_u64 v[40:41], v[36:37], 0, s[58:59]
	global_load_dword v109, v[40:41], off
	global_load_dword v125, v[60:61], off offset:8
	v_lshl_add_u64 v[40:41], v[34:35], 0, s[58:59]
	global_load_dword v110, v[40:41], off
	global_load_dword v126, v[60:61], off offset:16
	v_lshl_add_u64 v[40:41], v[32:33], 0, s[58:59]
	global_load_dword v111, v[40:41], off
	global_load_dword v127, v[60:61], off offset:24
	v_lshl_add_u64 v[40:41], v[30:31], 0, s[58:59]
	global_load_dword v112, v[40:41], off
	global_load_dword v128, v[60:61], off offset:32
	v_lshl_add_u64 v[40:41], v[28:29], 0, s[58:59]
	global_load_dword v113, v[40:41], off
	global_load_dword v129, v[60:61], off offset:40
	v_lshl_add_u64 v[40:41], v[26:27], 0, s[58:59]
	global_load_dword v114, v[40:41], off
	global_load_dword v130, v[60:61], off offset:48
	v_lshl_add_u64 v[40:41], v[22:23], 0, s[58:59]
	global_load_dword v115, v[40:41], off
	global_load_dword v131, v[60:61], off offset:56
	s_add_u32 s58, s58, 0x20000
	s_addc_u32 s59, s59, 0
	s_add_u32 s62, s62, 64
	s_addc_u32 s63, s63, 0
	s_waitcnt vmcnt(30)
	v_mul_f32_e32 v100, v100, v116
	ds_write_b32 v56, v100
	s_waitcnt vmcnt(28)
	v_mul_f32_e32 v101, v101, v117
	ds_write_b32 v56, v101 offset:264
	s_waitcnt vmcnt(26)
	v_mul_f32_e32 v102, v102, v118
	ds_write_b32 v56, v102 offset:528
	s_waitcnt vmcnt(24)
	v_mul_f32_e32 v103, v103, v119
	ds_write_b32 v56, v103 offset:792
	s_waitcnt vmcnt(22)
	v_mul_f32_e32 v104, v104, v120
	ds_write_b32 v56, v104 offset:1056
	s_waitcnt vmcnt(20)
	v_mul_f32_e32 v105, v105, v121
	ds_write_b32 v56, v105 offset:1320
	s_waitcnt vmcnt(18)
	v_mul_f32_e32 v106, v106, v122
	ds_write_b32 v56, v106 offset:1584
	s_waitcnt vmcnt(16)
	v_mul_f32_e32 v107, v107, v123
	ds_write_b32 v56, v107 offset:1848
	s_waitcnt vmcnt(14)
	v_mul_f32_e32 v108, v108, v124
	ds_write_b32 v56, v108 offset:2112
	s_waitcnt vmcnt(12)
	v_mul_f32_e32 v109, v109, v125
	ds_write_b32 v56, v109 offset:2376
	s_waitcnt vmcnt(10)
	v_mul_f32_e32 v110, v110, v126
	ds_write_b32 v56, v110 offset:2640
	s_waitcnt vmcnt(8)
	v_mul_f32_e32 v111, v111, v127
	ds_write_b32 v56, v111 offset:2904
	s_waitcnt vmcnt(6)
	v_mul_f32_e32 v112, v112, v128
	ds_write_b32 v56, v112 offset:3168
	s_waitcnt vmcnt(4)
	v_mul_f32_e32 v113, v113, v129
	ds_write_b32 v56, v113 offset:3432
	s_waitcnt vmcnt(2)
	v_mul_f32_e32 v114, v114, v130
	ds_write_b32 v56, v114 offset:3696
	s_waitcnt vmcnt(0)
; __device__ __forceinline__ void transpose_item(const float* __restrict__ W, int K, int N, int NV, bf16_t* __restrict__ WT, LAS float* scr, int item, int nblk, int lane, int mode, const float* __restrict__ kscale) {
;     ...
;     for (int i = 0; i < 32; ++i) { const int kk = 2 * i + (lane >> 5); float v = valid ? W[(size_t)(k0 + kk) * N + ns] : 0.f; if (kscale) v *= kscale[k0 + kk]; scr[kk * 33 + (lane & 31)] = v; }
	v_mul_f32_e32 v115, v115, v131
	ds_write_b32 v56, v115 offset:3960
	v_lshl_add_u64 v[60:61], s[62:63], 0, v[24:25]
	v_lshl_add_u64 v[40:41], v[38:39], 0, s[58:59]
	global_load_dword v100, v[40:41], off
	v_lshl_add_u64 v[58:59], s[62:63], 0, v[6:7]
	global_load_dword v116, v[58:59], off
	v_lshl_add_u64 v[40:41], v[36:37], 0, s[58:59]
	global_load_dword v101, v[40:41], off
	global_load_dword v117, v[60:61], off offset:8
	v_lshl_add_u64 v[40:41], v[34:35], 0, s[58:59]
	global_load_dword v102, v[40:41], off
	global_load_dword v118, v[60:61], off offset:16
	v_lshl_add_u64 v[40:41], v[32:33], 0, s[58:59]
	global_load_dword v103, v[40:41], off
	global_load_dword v119, v[60:61], off offset:24
	v_lshl_add_u64 v[40:41], v[30:31], 0, s[58:59]
	global_load_dword v104, v[40:41], off
	global_load_dword v120, v[60:61], off offset:32
	v_lshl_add_u64 v[40:41], v[28:29], 0, s[58:59]
	global_load_dword v105, v[40:41], off
	global_load_dword v121, v[60:61], off offset:40
	v_lshl_add_u64 v[40:41], v[26:27], 0, s[58:59]
	global_load_dword v106, v[40:41], off
	global_load_dword v122, v[60:61], off offset:48
	v_lshl_add_u64 v[40:41], v[22:23], 0, s[58:59]
	global_load_dword v107, v[40:41], off
	global_load_dword v123, v[60:61], off offset:56
	s_add_u32 s58, s58, 0x20000
	s_addc_u32 s59, s59, 0
	s_add_u32 s62, s62, 64
	s_addc_u32 s63, s63, 0
	v_lshl_add_u64 v[60:61], s[62:63], 0, v[24:25]
	v_lshl_add_u64 v[40:41], v[38:39], 0, s[58:59]
	global_load_dword v108, v[40:41], off
	v_lshl_add_u64 v[58:59], s[62:63], 0, v[6:7]
	global_load_dword v124, v[58:59], off
	v_lshl_add_u64 v[40:41], v[36:37], 0, s[58:59]
	global_load_dword v109, v[40:41], off
	global_load_dword v125, v[60:61], off offset:8
	v_lshl_add_u64 v[40:41], v[34:35], 0, s[58:59]
	global_load_dword v110, v[40:41], off
	global_load_dword v126, v[60:61], off offset:16
	v_lshl_add_u64 v[40:41], v[32:33], 0, s[58:59]
	global_load_dword v111, v[40:41], off
	global_load_dword v127, v[60:61], off offset:24
	v_lshl_add_u64 v[40:41], v[30:31], 0, s[58:59]
	global_load_dword v112, v[40:41], off
	global_load_dword v128, v[60:61], off offset:32
	v_lshl_add_u64 v[40:41], v[28:29], 0, s[58:59]
	global_load_dword v113, v[40:41], off
	global_load_dword v129, v[60:61], off offset:40
	v_lshl_add_u64 v[40:41], v[26:27], 0, s[58:59]
	global_load_dword v114, v[40:41], off
	global_load_dword v130, v[60:61], off offset:48
	v_lshl_add_u64 v[40:41], v[22:23], 0, s[58:59]
	global_load_dword v115, v[40:41], off
	global_load_dword v131, v[60:61], off offset:56
	s_add_u32 s58, s58, 0x20000
	s_addc_u32 s59, s59, 0
	s_add_u32 s62, s62, 64
	s_addc_u32 s63, s63, 0
	s_waitcnt vmcnt(30)
	v_mul_f32_e32 v100, v100, v116
	ds_write_b32 v56, v100 offset:4224
	s_waitcnt vmcnt(28)
	v_mul_f32_e32 v101, v101, v117
	ds_write_b32 v56, v101 offset:4488
	s_waitcnt vmcnt(26)
	v_mul_f32_e32 v102, v102, v118
	ds_write_b32 v56, v102 offset:4752
	s_waitcnt vmcnt(24)
	v_mul_f32_e32 v103, v103, v119
	ds_write_b32 v56, v103 offset:5016
	s_waitcnt vmcnt(22)
	v_mul_f32_e32 v104, v104, v120
	ds_write_b32 v56, v104 offset:5280
	s_waitcnt vmcnt(20)
	v_mul_f32_e32 v105, v105, v121
	ds_write_b32 v56, v105 offset:5544
	s_waitcnt vmcnt(18)
	v_mul_f32_e32 v106, v106, v122
	ds_write_b32 v56, v106 offset:5808
	s_waitcnt vmcnt(16)
	v_mul_f32_e32 v107, v107, v123
	ds_write_b32 v56, v107 offset:6072
	s_waitcnt vmcnt(14)
	v_mul_f32_e32 v108, v108, v124
	ds_write_b32 v56, v108 offset:6336
	s_waitcnt vmcnt(12)
	v_mul_f32_e32 v109, v109, v125
	ds_write_b32 v56, v109 offset:6600
	s_waitcnt vmcnt(10)
	v_mul_f32_e32 v110, v110, v126
	ds_write_b32 v56, v110 offset:6864
	s_waitcnt vmcnt(8)
	v_mul_f32_e32 v111, v111, v127
	ds_write_b32 v56, v111 offset:7128
	s_waitcnt vmcnt(6)
	v_mul_f32_e32 v112, v112, v128
	ds_write_b32 v56, v112 offset:7392
	s_waitcnt vmcnt(4)
	v_mul_f32_e32 v113, v113, v129
	ds_write_b32 v56, v113 offset:7656
	s_waitcnt vmcnt(2)
	v_mul_f32_e32 v114, v114, v130
	ds_write_b32 v56, v114 offset:7920
	s_waitcnt vmcnt(0)
	v_mul_f32_e32 v115, v115, v131
	ds_write_b32 v56, v115 offset:8184
	s_branch .LBB0_99

; __device__ __forceinline__ void transpose_item(const float* __restrict__ W, int K, int N, int NV, bf16_t* __restrict__ WT, LAS float* scr, int item, int nblk, int lane, int mode, const float* __restrict__ kscale) {
;     const int kb = item / nblk, nb = item % nblk, k0 = 64 * kb, n0 = 32 * nb;
;     const int nd = n0 + (lane & 31); const bool valid = nd < NV; const int ns = valid ? srccol(mode, nd) : 0;
; #pragma unroll 8
;     for (int i = 0; i < 32; ++i) { const int kk = 2 * i + (lane >> 5); float v = valid ? W[(size_t)(k0 + kk) * N + ns] : 0.f; if (kscale) v *= kscale[k0 + kk]; scr[kk * 33 + (lane & 31)] = v; }
.LBB0_105:
.LBB0_106:
	v_lshl_add_u64 v[60:61], s[62:63], 0, v[24:25]
	v_lshl_add_u64 v[40:41], v[38:39], 0, s[58:59]
	global_load_dword v100, v[40:41], off
	v_lshl_add_u64 v[58:59], s[62:63], 0, v[6:7]
	global_load_dword v116, v[58:59], off
	v_lshl_add_u64 v[40:41], v[36:37], 0, s[58:59]
	global_load_dword v101, v[40:41], off
	global_load_dword v117, v[60:61], off offset:8
	v_lshl_add_u64 v[40:41], v[34:35], 0, s[58:59]
	global_load_dword v102, v[40:41], off
	global_load_dword v118, v[60:61], off offset:16
	v_lshl_add_u64 v[40:41], v[32:33], 0, s[58:59]
	global_load_dword v103, v[40:41], off
	global_load_dword v119, v[60:61], off offset:24
	v_lshl_add_u64 v[40:41], v[30:31], 0, s[58:59]
	global_load_dword v104, v[40:41], off
	global_load_dword v120, v[60:61], off offset:32
	v_lshl_add_u64 v[40:41], v[28:29], 0, s[58:59]
	global_load_dword v105, v[40:41], off
	global_load_dword v121, v[60:61], off offset:40
	v_lshl_add_u64 v[40:41], v[26:27], 0, s[58:59]
	global_load_dword v106, v[40:41], off
	global_load_dword v122, v[60:61], off offset:48
	v_lshl_add_u64 v[40:41], v[22:23], 0, s[58:59]
	global_load_dword v107, v[40:41], off
	global_load_dword v123, v[60:61], off offset:56
	s_add_u32 s58, s58, 0x18000
	s_addc_u32 s59, s59, 0
	s_add_u32 s62, s62, 64
	s_addc_u32 s63, s63, 0
	v_lshl_add_u64 v[60:61], s[62:63], 0, v[24:25]
	v_lshl_add_u64 v[40:41], v[38:39], 0, s[58:59]
	global_load_dword v108, v[40:41], off
	v_lshl_add_u64 v[58:59], s[62:63], 0, v[6:7]
	global_load_dword v124, v[58:59], off
	v_lshl_add_u64 v[40:41], v[36:37], 0, s[58:59]
	global_load_dword v109, v[40:41], off
	global_load_dword v125, v[60:61], off offset:8
	v_lshl_add_u64 v[40:41], v[34:35], 0, s[58:59]
	global_load_dword v110, v[40:41], off
	global_load_dword v126, v[60:61], off offset:16
	v_lshl_add_u64 v[40:41], v[32:33], 0, s[58:59]
	global_load_dword v111, v[40:41], off
	global_load_dword v127, v[60:61], off offset:24
	v_lshl_add_u64 v[40:41], v[30:31], 0, s[58:59]
	global_load_dword v112, v[40:41], off
	global_load_dword v128, v[60:61], off offset:32
	v_lshl_add_u64 v[40:41], v[28:29], 0, s[58:59]
	global_load_dword v113, v[40:41], off
	global_load_dword v129, v[60:61], off offset:40
	v_lshl_add_u64 v[40:41], v[26:27], 0, s[58:59]
	global_load_dword v114, v[40:41], off
	global_load_dword v130, v[60:61], off offset:48
	v_lshl_add_u64 v[40:41], v[22:23], 0, s[58:59]
	global_load_dword v115, v[40:41], off
	global_load_dword v131, v[60:61], off offset:56
	s_add_u32 s58, s58, 0x18000
	s_addc_u32 s59, s59, 0
	s_add_u32 s62, s62, 64
	s_addc_u32 s63, s63, 0
	s_waitcnt vmcnt(30)
	v_mul_f32_e32 v100, v100, v116
	ds_write_b32 v56, v100
	s_waitcnt vmcnt(28)
	v_mul_f32_e32 v101, v101, v117
	ds_write_b32 v56, v101 offset:264
	s_waitcnt vmcnt(26)
	v_mul_f32_e32 v102, v102, v118
	ds_write_b32 v56, v102 offset:528
	s_waitcnt vmcnt(24)
	v_mul_f32_e32 v103, v103, v119
	ds_write_b32 v56, v103 offset:792
	s_waitcnt vmcnt(22)
	v_mul_f32_e32 v104, v104, v120
	ds_write_b32 v56, v104 offset:1056
	s_waitcnt vmcnt(20)
	v_mul_f32_e32 v105, v105, v121
	ds_write_b32 v56, v105 offset:1320
	s_waitcnt vmcnt(18)
	v_mul_f32_e32 v106, v106, v122
	ds_write_b32 v56, v106 offset:1584
	s_waitcnt vmcnt(16)
	v_mul_f32_e32 v107, v107, v123
	ds_write_b32 v56, v107 offset:1848
	s_waitcnt vmcnt(14)
	v_mul_f32_e32 v108, v108, v124
	ds_write_b32 v56, v108 offset:2112
	s_waitcnt vmcnt(12)
	v_mul_f32_e32 v109, v109, v125
	ds_write_b32 v56, v109 offset:2376
	s_waitcnt vmcnt(10)
	v_mul_f32_e32 v110, v110, v126
	ds_write_b32 v56, v110 offset:2640
	s_waitcnt vmcnt(8)
	v_mul_f32_e32 v111, v111, v127
	ds_write_b32 v56, v111 offset:2904
	s_waitcnt vmcnt(6)
	v_mul_f32_e32 v112, v112, v128
	ds_write_b32 v56, v112 offset:3168
	s_waitcnt vmcnt(4)
	v_mul_f32_e32 v113, v113, v129
	ds_write_b32 v56, v113 offset:3432
	s_waitcnt vmcnt(2)
	v_mul_f32_e32 v114, v114, v130
	ds_write_b32 v56, v114 offset:3696
	s_waitcnt vmcnt(0)
; __device__ __forceinline__ void transpose_item(const float* __restrict__ W, int K, int N, int NV, bf16_t* __restrict__ WT, LAS float* scr, int item, int nblk, int lane, int mode, const float* __restrict__ kscale) {
;     ...
;     for (int i = 0; i < 32; ++i) { const int kk = 2 * i + (lane >> 5); float v = valid ? W[(size_t)(k0 + kk) * N + ns] : 0.f; if (kscale) v *= kscale[k0 + kk]; scr[kk * 33 + (lane & 31)] = v; }
	v_mul_f32_e32 v115, v115, v131
	ds_write_b32 v56, v115 offset:3960
	v_lshl_add_u64 v[60:61], s[62:63], 0, v[24:25]
	v_lshl_add_u64 v[40:41], v[38:39], 0, s[58:59]
	global_load_dword v100, v[40:41], off
	v_lshl_add_u64 v[58:59], s[62:63], 0, v[6:7]
	global_load_dword v116, v[58:59], off
	v_lshl_add_u64 v[40:41], v[36:37], 0, s[58:59]
	global_load_dword v101, v[40:41], off
	global_load_dword v117, v[60:61], off offset:8
	v_lshl_add_u64 v[40:41], v[34:35], 0, s[58:59]
	global_load_dword v102, v[40:41], off
	global_load_dword v118, v[60:61], off offset:16
	v_lshl_add_u64 v[40:41], v[32:33], 0, s[58:59]
	global_load_dword v103, v[40:41], off
	global_load_dword v119, v[60:61], off offset:24
	v_lshl_add_u64 v[40:41], v[30:31], 0, s[58:59]
	global_load_dword v104, v[40:41], off
	global_load_dword v120, v[60:61], off offset:32
	v_lshl_add_u64 v[40:41], v[28:29], 0, s[58:59]
	global_load_dword v105, v[40:41], off
	global_load_dword v121, v[60:61], off offset:40
	v_lshl_add_u64 v[40:41], v[26:27], 0, s[58:59]
	global_load_dword v106, v[40:41], off
	global_load_dword v122, v[60:61], off offset:48
	v_lshl_add_u64 v[40:41], v[22:23], 0, s[58:59]
	global_load_dword v107, v[40:41], off
	global_load_dword v123, v[60:61], off offset:56
	s_add_u32 s58, s58, 0x18000
	s_addc_u32 s59, s59, 0
	s_add_u32 s62, s62, 64
	s_addc_u32 s63, s63, 0
	v_lshl_add_u64 v[60:61], s[62:63], 0, v[24:25]
	v_lshl_add_u64 v[40:41], v[38:39], 0, s[58:59]
	global_load_dword v108, v[40:41], off
	v_lshl_add_u64 v[58:59], s[62:63], 0, v[6:7]
	global_load_dword v124, v[58:59], off
	v_lshl_add_u64 v[40:41], v[36:37], 0, s[58:59]
	global_load_dword v109, v[40:41], off
	global_load_dword v125, v[60:61], off offset:8
	v_lshl_add_u64 v[40:41], v[34:35], 0, s[58:59]
	global_load_dword v110, v[40:41], off
	global_load_dword v126, v[60:61], off offset:16
	v_lshl_add_u64 v[40:41], v[32:33], 0, s[58:59]
	global_load_dword v111, v[40:41], off
	global_load_dword v127, v[60:61], off offset:24
	v_lshl_add_u64 v[40:41], v[30:31], 0, s[58:59]
	global_load_dword v112, v[40:41], off
	global_load_dword v128, v[60:61], off offset:32
	v_lshl_add_u64 v[40:41], v[28:29], 0, s[58:59]
	global_load_dword v113, v[40:41], off
	global_load_dword v129, v[60:61], off offset:40
	v_lshl_add_u64 v[40:41], v[26:27], 0, s[58:59]
	global_load_dword v114, v[40:41], off
	global_load_dword v130, v[60:61], off offset:48
	v_lshl_add_u64 v[40:41], v[22:23], 0, s[58:59]
	global_load_dword v115, v[40:41], off
	global_load_dword v131, v[60:61], off offset:56
	s_add_u32 s58, s58, 0x18000
	s_addc_u32 s59, s59, 0
	s_add_u32 s62, s62, 64
	s_addc_u32 s63, s63, 0
	s_waitcnt vmcnt(30)
	v_mul_f32_e32 v100, v100, v116
	ds_write_b32 v56, v100 offset:4224
	s_waitcnt vmcnt(28)
	v_mul_f32_e32 v101, v101, v117
	ds_write_b32 v56, v101 offset:4488
	s_waitcnt vmcnt(26)
	v_mul_f32_e32 v102, v102, v118
	ds_write_b32 v56, v102 offset:4752
	s_waitcnt vmcnt(24)
	v_mul_f32_e32 v103, v103, v119
	ds_write_b32 v56, v103 offset:5016
	s_waitcnt vmcnt(22)
	v_mul_f32_e32 v104, v104, v120
	ds_write_b32 v56, v104 offset:5280
	s_waitcnt vmcnt(20)
	v_mul_f32_e32 v105, v105, v121
	ds_write_b32 v56, v105 offset:5544
	s_waitcnt vmcnt(18)
	v_mul_f32_e32 v106, v106, v122
	ds_write_b32 v56, v106 offset:5808
	s_waitcnt vmcnt(16)
	v_mul_f32_e32 v107, v107, v123
	ds_write_b32 v56, v107 offset:6072
	s_waitcnt vmcnt(14)
	v_mul_f32_e32 v108, v108, v124
	ds_write_b32 v56, v108 offset:6336
	s_waitcnt vmcnt(12)
	v_mul_f32_e32 v109, v109, v125
	ds_write_b32 v56, v109 offset:6600
	s_waitcnt vmcnt(10)
	v_mul_f32_e32 v110, v110, v126
	ds_write_b32 v56, v110 offset:6864
	s_waitcnt vmcnt(8)
	v_mul_f32_e32 v111, v111, v127
	ds_write_b32 v56, v111 offset:7128
	s_waitcnt vmcnt(6)
	v_mul_f32_e32 v112, v112, v128
	ds_write_b32 v56, v112 offset:7392
	s_waitcnt vmcnt(4)
	v_mul_f32_e32 v113, v113, v129
	ds_write_b32 v56, v113 offset:7656
	s_waitcnt vmcnt(2)
	v_mul_f32_e32 v114, v114, v130
	ds_write_b32 v56, v114 offset:7920
	s_waitcnt vmcnt(0)
	v_mul_f32_e32 v115, v115, v131
	ds_write_b32 v56, v115 offset:8184
	s_branch .LBB0_122

; __device__ __forceinline__ void transpose_item(const float* __restrict__ W, int K, int N, int NV, bf16_t* __restrict__ WT, LAS float* scr, int item, int nblk, int lane, int mode, const float* __restrict__ kscale) {
;     ...
;     const int nd = n0 + (lane & 31); const bool valid = nd < NV; const int ns = valid ? srccol(mode, nd) : 0;
; #pragma unroll 8
;     for (int i = 0; i < 32; ++i) { const int kk = 2 * i + (lane >> 5); float v = valid ? W[(size_t)(k0 + kk) * N + ns] : 0.f; if (kscale) v *= kscale[k0 + kk]; scr[kk * 33 + (lane & 31)] = v; }
.LBB0_130:
.LBB0_131:
	v_mov_b32_e32 v100, 0
	v_mov_b32_e32 v101, 0
	v_mov_b32_e32 v102, 0
	v_mov_b32_e32 v103, 0
	v_mov_b32_e32 v104, 0
	v_mov_b32_e32 v105, 0
	v_mov_b32_e32 v106, 0
	v_mov_b32_e32 v107, 0
	v_mov_b32_e32 v108, 0
	v_mov_b32_e32 v109, 0
	v_mov_b32_e32 v110, 0
	v_mov_b32_e32 v111, 0
	v_mov_b32_e32 v112, 0
	v_mov_b32_e32 v113, 0
	v_mov_b32_e32 v114, 0
	v_mov_b32_e32 v115, 0
	v_mov_b32_e32 v116, 0
	v_mov_b32_e32 v117, 0
	v_mov_b32_e32 v118, 0
	v_mov_b32_e32 v119, 0
	v_mov_b32_e32 v120, 0
	v_mov_b32_e32 v121, 0
	v_mov_b32_e32 v122, 0
	v_mov_b32_e32 v123, 0
	v_mov_b32_e32 v124, 0
	v_mov_b32_e32 v125, 0
	v_mov_b32_e32 v126, 0
	v_mov_b32_e32 v127, 0
	v_mov_b32_e32 v128, 0
	v_mov_b32_e32 v129, 0
	v_mov_b32_e32 v130, 0
	v_mov_b32_e32 v131, 0
	s_and_saveexec_b64 s[58:59], vcc
	v_mov_b32_e32 v26, v6
	v_mad_i64_i32 v[26:27], s[62:63], v26, s81, v[22:23]
	global_load_dword v100, v[26:27], off
	v_add_u32_e32 v26, 2, v6
	v_mad_i64_i32 v[26:27], s[62:63], v26, s81, v[22:23]
	global_load_dword v101, v[26:27], off
	v_add_u32_e32 v26, 4, v6
	v_mad_i64_i32 v[26:27], s[62:63], v26, s81, v[22:23]
	global_load_dword v102, v[26:27], off
	v_add_u32_e32 v26, 6, v6
	v_mad_i64_i32 v[26:27], s[62:63], v26, s81, v[22:23]
	global_load_dword v103, v[26:27], off
	v_add_u32_e32 v26, 8, v6
	v_mad_i64_i32 v[26:27], s[62:63], v26, s81, v[22:23]
	global_load_dword v104, v[26:27], off
	v_add_u32_e32 v26, 10, v6
	v_mad_i64_i32 v[26:27], s[62:63], v26, s81, v[22:23]
	global_load_dword v105, v[26:27], off
	v_add_u32_e32 v26, 12, v6
	v_mad_i64_i32 v[26:27], s[62:63], v26, s81, v[22:23]
	global_load_dword v106, v[26:27], off
	v_add_u32_e32 v26, 14, v6
	v_mad_i64_i32 v[26:27], s[62:63], v26, s81, v[22:23]
	global_load_dword v107, v[26:27], off
	v_add_u32_e32 v26, 16, v6
	v_mad_i64_i32 v[26:27], s[62:63], v26, s81, v[22:23]
	global_load_dword v108, v[26:27], off
	v_add_u32_e32 v26, 18, v6
	v_mad_i64_i32 v[26:27], s[62:63], v26, s81, v[22:23]
	global_load_dword v109, v[26:27], off
	v_add_u32_e32 v26, 20, v6
	v_mad_i64_i32 v[26:27], s[62:63], v26, s81, v[22:23]
	global_load_dword v110, v[26:27], off
	v_add_u32_e32 v26, 22, v6
	v_mad_i64_i32 v[26:27], s[62:63], v26, s81, v[22:23]
	global_load_dword v111, v[26:27], off
	v_add_u32_e32 v26, 24, v6
	v_mad_i64_i32 v[26:27], s[62:63], v26, s81, v[22:23]
	global_load_dword v112, v[26:27], off
	v_add_u32_e32 v26, 26, v6
	v_mad_i64_i32 v[26:27], s[62:63], v26, s81, v[22:23]
	global_load_dword v113, v[26:27], off
	v_add_u32_e32 v26, 28, v6
	v_mad_i64_i32 v[26:27], s[62:63], v26, s81, v[22:23]
	global_load_dword v114, v[26:27], off
	v_add_u32_e32 v26, 30, v6
	v_mad_i64_i32 v[26:27], s[62:63], v26, s81, v[22:23]
	global_load_dword v115, v[26:27], off
	v_add_u32_e32 v26, 32, v6
	v_mad_i64_i32 v[26:27], s[62:63], v26, s81, v[22:23]
	global_load_dword v116, v[26:27], off
	v_add_u32_e32 v26, 34, v6
	v_mad_i64_i32 v[26:27], s[62:63], v26, s81, v[22:23]
	global_load_dword v117, v[26:27], off
	v_add_u32_e32 v26, 36, v6
	v_mad_i64_i32 v[26:27], s[62:63], v26, s81, v[22:23]
	global_load_dword v118, v[26:27], off
	v_add_u32_e32 v26, 38, v6
	v_mad_i64_i32 v[26:27], s[62:63], v26, s81, v[22:23]
	global_load_dword v119, v[26:27], off
	v_add_u32_e32 v26, 40, v6
	v_mad_i64_i32 v[26:27], s[62:63], v26, s81, v[22:23]
	global_load_dword v120, v[26:27], off
	v_add_u32_e32 v26, 42, v6
	v_mad_i64_i32 v[26:27], s[62:63], v26, s81, v[22:23]
	global_load_dword v121, v[26:27], off
	v_add_u32_e32 v26, 44, v6
	v_mad_i64_i32 v[26:27], s[62:63], v26, s81, v[22:23]
	global_load_dword v122, v[26:27], off
	v_add_u32_e32 v26, 46, v6
	v_mad_i64_i32 v[26:27], s[62:63], v26, s81, v[22:23]
	global_load_dword v123, v[26:27], off
	v_add_u32_e32 v26, 48, v6
	v_mad_i64_i32 v[26:27], s[62:63], v26, s81, v[22:23]
	global_load_dword v124, v[26:27], off
	v_add_u32_e32 v26, 50, v6
	v_mad_i64_i32 v[26:27], s[62:63], v26, s81, v[22:23]
	global_load_dword v125, v[26:27], off
	v_add_u32_e32 v26, 52, v6
	v_mad_i64_i32 v[26:27], s[62:63], v26, s81, v[22:23]
	global_load_dword v126, v[26:27], off
	v_add_u32_e32 v26, 54, v6
	v_mad_i64_i32 v[26:27], s[62:63], v26, s81, v[22:23]
	global_load_dword v127, v[26:27], off
	v_add_u32_e32 v26, 56, v6
	v_mad_i64_i32 v[26:27], s[62:63], v26, s81, v[22:23]
	global_load_dword v128, v[26:27], off
	v_add_u32_e32 v26, 58, v6
	v_mad_i64_i32 v[26:27], s[62:63], v26, s81, v[22:23]
	global_load_dword v129, v[26:27], off
	v_add_u32_e32 v26, 60, v6
	v_mad_i64_i32 v[26:27], s[62:63], v26, s81, v[22:23]
	global_load_dword v130, v[26:27], off
	v_add_u32_e32 v26, 62, v6
	v_mad_i64_i32 v[26:27], s[62:63], v26, s81, v[22:23]
	global_load_dword v131, v[26:27], off
	s_or_b64 exec, exec, s[58:59]
	s_waitcnt vmcnt(31)
	ds_write_b32 v24, v100
	s_waitcnt vmcnt(30)
	ds_write_b32 v24, v101 offset:264
	s_waitcnt vmcnt(29)
	ds_write_b32 v24, v102 offset:528
	s_waitcnt vmcnt(28)
	ds_write_b32 v24, v103 offset:792
	s_waitcnt vmcnt(27)
	ds_write_b32 v24, v104 offset:1056
	s_waitcnt vmcnt(26)
	ds_write_b32 v24, v105 offset:1320
	s_waitcnt vmcnt(25)
	ds_write_b32 v24, v106 offset:1584
	s_waitcnt vmcnt(24)
	ds_write_b32 v24, v107 offset:1848
	s_waitcnt vmcnt(23)
	ds_write_b32 v24, v108 offset:2112
	s_waitcnt vmcnt(22)
	ds_write_b32 v24, v109 offset:2376
	s_waitcnt vmcnt(21)
	ds_write_b32 v24, v110 offset:2640
	s_waitcnt vmcnt(20)
	ds_write_b32 v24, v111 offset:2904
	s_waitcnt vmcnt(19)
	ds_write_b32 v24, v112 offset:3168
	s_waitcnt vmcnt(18)
	ds_write_b32 v24, v113 offset:3432
	s_waitcnt vmcnt(17)
	ds_write_b32 v24, v114 offset:3696
	s_waitcnt vmcnt(16)
	ds_write_b32 v24, v115 offset:3960
	s_waitcnt vmcnt(15)
	ds_write_b32 v24, v116 offset:4224
	s_waitcnt vmcnt(14)
	ds_write_b32 v24, v117 offset:4488
	s_waitcnt vmcnt(13)
	ds_write_b32 v24, v118 offset:4752
	s_waitcnt vmcnt(12)
	ds_write_b32 v24, v119 offset:5016
	s_waitcnt vmcnt(11)
	ds_write_b32 v24, v120 offset:5280
	s_waitcnt vmcnt(10)
	ds_write_b32 v24, v121 offset:5544
	s_waitcnt vmcnt(9)
	ds_write_b32 v24, v122 offset:5808
	s_waitcnt vmcnt(8)
	ds_write_b32 v24, v123 offset:6072
	s_waitcnt vmcnt(7)
	ds_write_b32 v24, v124 offset:6336
	s_waitcnt vmcnt(6)
	ds_write_b32 v24, v125 offset:6600
	s_waitcnt vmcnt(5)
	ds_write_b32 v24, v126 offset:6864
	s_waitcnt vmcnt(4)
	ds_write_b32 v24, v127 offset:7128
	s_waitcnt vmcnt(3)
	ds_write_b32 v24, v128 offset:7392
	s_waitcnt vmcnt(2)
	ds_write_b32 v24, v129 offset:7656
	s_waitcnt vmcnt(1)
	ds_write_b32 v24, v130 offset:7920
	s_waitcnt vmcnt(0)
	ds_write_b32 v24, v131 offset:8184
	s_branch .LBB0_46
